# leader write-back also skipped after the initial post phase and after the last layer's in-proj GEMM (both all write-through)
# speedup vs baseline: 1.0124x; 1.0124x over previous
.Lxb_leader:
	v_readlane_b32 s98, v252, 2
	s_nop 0
	s_sub_i32 s98, s98, 4
	s_cmp_eq_u32 s98, -1
	s_cbranch_scc1 .Lxb_noflush
	s_cmp_eq_u32 s98, 33
	s_cbranch_scc1 .Lxb_noflush
	s_cmp_lt_i32 s98, 0
	s_cbranch_scc1 .Lxb_flush
	s_mul_i32 s99, s98, 0x1746
	s_lshr_b32 s99, s99, 16
	s_mul_i32 s99, s99, 11
	s_sub_i32 s98, s98, s99
	s_lshl_b32 s98, 1, s98
	s_and_b32 s98, s98, 0x6e0
	s_cmp_lg_u32 s98, 0
	s_cbranch_scc1 .Lxb_noflush
